# attention stagger: map-1 waves sleep 256 cycles per step instead of 512
# speedup vs baseline: 1.0123x; 1.0084x over previous
.LBB0_310:
	s_and_b64 vcc, exec, s[40:41]
	s_cbranch_vccz .Lat_nostag
	s_sleep 4
